# norm loops: all 16 row/gain/shift/scale loads issued up front with counted waits (4 own-phase norm loops) + final norm rewritten with hoisted gain and paired-row prefetch, on the v27 stack
# speedup vs baseline: 1.0145x; 1.0021x over previous
; __device__ __forceinline__ unsigned pk2(float lo, float hi) { f32x2_pk v = {lo, hi}; bf16x2_pk b = __builtin_convertvector(v, bf16x2_pk); return __builtin_bit_cast(unsigned, b); }
; __device__ __forceinline__ void norm_phase(const float* xl, const float* xc, const float* g, const float* shift, const float* scale, bf16_t* Z, int row_lo, int nrows, int gw, int ngw, int lane) {
;     for (int m = row_lo + gw; m < nrows; m += ngw) {
;         const float* xr = m < ML ? xl + (size_t)m * D : xc + (size_t)(m - ML) * D; const int mr = m < ML ? (m >> 11) : 16;
;         f32x4 v[4]; float ss = 0.f;
; #pragma unroll
;         for (int j = 0; j < 4; ++j) { v[j] = *(const f32x4*)(xr + 4 * lane + 256 * j); ss += (v[j].x * v[j].x + v[j].y * v[j].y) + (v[j].z * v[j].z + v[j].w * v[j].w); }
;         const float ri = rsqrtf(wave_sum(ss) * (1.0f / D) + 1e-6f);
; #pragma unroll
;         for (int j = 0; j < 4; ++j) { const int c = 4 * lane + 256 * j; const f32x4 gv = *(const f32x4*)(g + c), sh = *(const f32x4*)(shift + (size_t)mr * 6144 + c), sc = *(const f32x4*)(scale + (size_t)mr * 6144 + c);
;             const f32x4 o = v[j] * ri * gv * (sc + 1.0f) + sh; u32x2 w; w.x = pk2(o.x, o.y); w.y = pk2(o.z, o.w); *(u32x2*)(Z + (size_t)m * D + c) = w; }
;     }
.LBB0_87:
	s_min_i32 s1, s6, 0x8000
	s_ashr_i32 s1, s1, 11
	global_load_dwordx4 v[64:67], v14, s[14:15]
	global_load_dwordx4 v[68:71], v14, s[14:15] offset:1024
	global_load_dwordx4 v[72:75], v14, s[14:15] offset:3072
	global_load_dwordx4 v[76:79], v14, s[14:15] offset:2048
	v_mad_i64_i32 v[80:81], s[2:3], s1, v212, v[4:5]
	global_load_dwordx4 v[84:87], v[80:81], off
	global_load_dwordx4 v[88:91], v[0:1], off
	v_mad_i64_i32 v[92:93], s[2:3], s1, v212, v[2:3]
	global_load_dwordx4 v[96:99], v[92:93], off
	global_load_dwordx4 v[100:103], v[0:1], off offset:1024
	global_load_dwordx4 v[104:107], v[80:81], off offset:1024
	global_load_dwordx4 v[108:111], v[92:93], off offset:1024
	global_load_dwordx4 v[112:115], v[0:1], off offset:2048
	global_load_dwordx4 v[116:119], v[80:81], off offset:2048
	global_load_dwordx4 v[120:123], v[92:93], off offset:2048
	global_load_dwordx4 v[124:127], v[0:1], off offset:3072
	global_load_dwordx4 v[128:131], v[80:81], off offset:3072
	global_load_dwordx4 v[132:135], v[92:93], off offset:3072
	s_lshl_b64 s[2:3], s[12:13], 11
	s_add_u32 s6, s6, s80
	s_addc_u32 s7, s7, s81
	s_add_u32 s10, s10, s48
	s_addc_u32 s11, s11, s49
	s_cmp_lt_i32 s6, 0x9000
	s_waitcnt vmcnt(15)
	v_pk_mul_f32 v[48:49], v[66:67], v[66:67]
	v_pk_mul_f32 v[50:51], v[64:65], v[64:65]
	s_waitcnt vmcnt(14)
	v_pk_mul_f32 v[52:53], v[70:71], v[70:71]
	v_pk_mul_f32 v[54:55], v[68:69], v[68:69]
	v_pk_mov_b32 v[60:61], v[50:51], v[48:49] op_sel:[1,0]
	v_mov_b32_e32 v51, v49
	v_pk_mov_b32 v[48:49], v[54:55], v[52:53] op_sel:[1,0]
	v_mov_b32_e32 v55, v53
	s_waitcnt vmcnt(13)
	v_mul_f32_e32 v59, v73, v73
	s_waitcnt vmcnt(12)
	v_mul_f32_e32 v56, v77, v77
	v_mul_f32_e32 v58, v79, v79
	v_pk_add_f32 v[50:51], v[60:61], v[50:51]
	v_pk_add_f32 v[48:49], v[48:49], v[54:55]
	v_mul_f32_e32 v15, v72, v72
	v_mul_f32_e32 v62, v74, v74
	v_mul_f32_e32 v63, v75, v75
	v_pk_fma_f32 v[52:53], v[76:77], v[76:77], v[56:57] op_sel_hi:[1,1,0]
	v_pk_fma_f32 v[56:57], v[78:79], v[78:79], v[58:59] op_sel_hi:[1,1,0]
	v_pk_add_f32 v[50:51], v[50:51], v[50:51] op_sel:[0,1] op_sel_hi:[1,0]
	v_pk_add_f32 v[48:49], v[48:49], v[48:49] op_sel:[0,1] op_sel_hi:[1,0]
	v_mov_b32_e32 v53, v62
	v_mov_b32_e32 v57, v63
	v_mov_b32_e32 v51, v15
	v_mov_b32_e32 v49, v59
	v_pk_add_f32 v[52:53], v[52:53], v[56:57]
	v_pk_add_f32 v[48:49], v[50:51], v[48:49]
	s_waitcnt vmcnt(11)
	v_pk_add_f32 v[86:87], v[86:87], 1.0 op_sel_hi:[1,0]
	v_pk_add_f32 v[48:49], v[48:49], v[52:53]
	v_pk_add_f32 v[84:85], v[84:85], 1.0 op_sel_hi:[1,0]
	v_add_f32_e32 v15, v48, v49
	s_nop 1
	v_add_f32_dpp v15, v15, v15 quad_perm:[1,0,3,2] row_mask:0xf bank_mask:0xf
	s_nop 1
	v_add_f32_dpp v15, v15, v15 quad_perm:[2,3,0,1] row_mask:0xf bank_mask:0xf
	s_nop 1
	v_add_f32_dpp v15, v15, v15 row_half_mirror row_mask:0xf bank_mask:0xf
	s_nop 1
	v_add_f32_dpp v15, v15, v15 row_mirror row_mask:0xf bank_mask:0xf
	v_mov_b32_e32 v48, v15
	s_nop 1
	v_permlane16_swap_b32_e32 v15, v48
	v_add_f32_e32 v15, v15, v48
	v_mov_b32_e32 v48, v15
	s_nop 1
	v_permlane32_swap_b32_e32 v15, v48
	v_add_f32_e32 v15, v15, v48
	s_waitcnt lgkmcnt(0)
	v_fmamk_f32 v15, v15, 0x3a800000, v199
	v_mul_f32_e32 v48, 0x4b800000, v15
	v_cmp_gt_f32_e32 vcc, s64, v15
	s_nop 1
	v_cndmask_b32_e32 v15, v15, v48, vcc
	v_rsq_f32_e32 v15, v15
	v_lshl_add_u64 v[48:49], v[6:7], 0, s[2:3]
	v_mul_f32_e32 v50, 0x45800000, v15
	v_cndmask_b32_e32 v50, v15, v50, vcc
	v_pk_mul_f32 v[66:67], v[66:67], v[50:51] op_sel_hi:[1,0]
	v_pk_mul_f32 v[64:65], v[64:65], v[50:51] op_sel_hi:[1,0]
	s_waitcnt vmcnt(10)
	v_pk_mul_f32 v[66:67], v[90:91], v[66:67]
	v_pk_mul_f32 v[64:65], v[88:89], v[64:65]
	s_waitcnt vmcnt(9)
	v_pk_fma_f32 v[66:67], v[86:87], v[66:67], v[98:99]
	v_pk_fma_f32 v[64:65], v[84:85], v[64:65], v[96:97]
	v_pk_mul_f32 v[70:71], v[70:71], v[50:51] op_sel_hi:[1,0]
	v_cvt_pk_bf16_f32 v64, v64, v65
	v_cvt_pk_bf16_f32 v65, v66, v67
	global_store_dwordx2 v[48:49], v[64:65], off
	s_nop 0
	v_pk_mul_f32 v[68:69], v[68:69], v[50:51] op_sel_hi:[1,0]
	v_pk_mul_f32 v[78:79], v[78:79], v[50:51] op_sel_hi:[1,0]
	v_pk_mul_f32 v[76:77], v[76:77], v[50:51] op_sel_hi:[1,0]
	v_pk_mul_f32 v[74:75], v[74:75], v[50:51] op_sel_hi:[1,0]
	v_pk_mul_f32 v[72:73], v[72:73], v[50:51] op_sel_hi:[1,0]
	s_waitcnt vmcnt(9)
	v_pk_mul_f32 v[100:101], v[100:101], v[68:69]
	v_pk_mul_f32 v[102:103], v[102:103], v[70:71]
	s_waitcnt vmcnt(8)
	v_pk_add_f32 v[68:69], v[106:107], 1.0 op_sel_hi:[1,0]
	v_pk_add_f32 v[70:71], v[104:105], 1.0 op_sel_hi:[1,0]
	s_waitcnt vmcnt(7)
	v_pk_fma_f32 v[102:103], v[68:69], v[102:103], v[110:111]
	v_pk_fma_f32 v[100:101], v[70:71], v[100:101], v[108:109]
	s_nop 0
	v_cvt_pk_bf16_f32 v100, v100, v101
	v_cvt_pk_bf16_f32 v101, v102, v103
	global_store_dwordx2 v[48:49], v[100:101], off offset:512
	s_nop 0
	s_waitcnt vmcnt(7)
	v_pk_mul_f32 v[112:113], v[112:113], v[76:77]
	v_pk_mul_f32 v[114:115], v[114:115], v[78:79]
	s_waitcnt vmcnt(6)
	v_pk_add_f32 v[118:119], v[118:119], 1.0 op_sel_hi:[1,0]
	v_pk_add_f32 v[116:117], v[116:117], 1.0 op_sel_hi:[1,0]
	s_waitcnt vmcnt(5)
	v_pk_fma_f32 v[114:115], v[118:119], v[114:115], v[122:123]
	v_pk_fma_f32 v[112:113], v[116:117], v[112:113], v[120:121]
	s_nop 0
	v_cvt_pk_bf16_f32 v112, v112, v113
	v_cvt_pk_bf16_f32 v113, v114, v115
	global_store_dwordx2 v[48:49], v[112:113], off offset:1024
	s_nop 0
	s_waitcnt vmcnt(5)
	v_pk_mul_f32 v[124:125], v[124:125], v[72:73]
	v_pk_mul_f32 v[126:127], v[126:127], v[74:75]
	s_waitcnt vmcnt(4)
	v_pk_add_f32 v[130:131], v[130:131], 1.0 op_sel_hi:[1,0]
	v_pk_add_f32 v[128:129], v[128:129], 1.0 op_sel_hi:[1,0]
	s_waitcnt vmcnt(3)
	v_pk_fma_f32 v[126:127], v[126:127], v[130:131], v[134:135]
	v_pk_fma_f32 v[124:125], v[124:125], v[128:129], v[132:133]
	s_nop 0
	v_cvt_pk_bf16_f32 v124, v124, v125
	v_cvt_pk_bf16_f32 v125, v126, v127
	global_store_dwordx2 v[48:49], v[124:125], off offset:1536
	s_cbranch_scc0 .LBB0_90

; __device__ __forceinline__ unsigned pk2(float lo, float hi) { f32x2_pk v = {lo, hi}; bf16x2_pk b = __builtin_convertvector(v, bf16x2_pk); return __builtin_bit_cast(unsigned, b); }
; __device__ __forceinline__ void norm_phase(const float* xl, const float* xc, const float* g, const float* shift, const float* scale, bf16_t* Z, int row_lo, int nrows, int gw, int ngw, int lane) {
;     for (int m = row_lo + gw; m < nrows; m += ngw) {
;         const float* xr = m < ML ? xl + (size_t)m * D : xc + (size_t)(m - ML) * D; const int mr = m < ML ? (m >> 11) : 16;
;         f32x4 v[4]; float ss = 0.f;
; #pragma unroll
;         for (int j = 0; j < 4; ++j) { v[j] = *(const f32x4*)(xr + 4 * lane + 256 * j); ss += (v[j].x * v[j].x + v[j].y * v[j].y) + (v[j].z * v[j].z + v[j].w * v[j].w); }
;         const float ri = rsqrtf(wave_sum(ss) * (1.0f / D) + 1e-6f);
; #pragma unroll
;         for (int j = 0; j < 4; ++j) { const int c = 4 * lane + 256 * j; const f32x4 gv = *(const f32x4*)(g + c), sh = *(const f32x4*)(shift + (size_t)mr * 6144 + c), sc = *(const f32x4*)(scale + (size_t)mr * 6144 + c);
;             const f32x4 o = v[j] * ri * gv * (sc + 1.0f) + sh; u32x2 w; w.x = pk2(o.x, o.y); w.y = pk2(o.z, o.w); *(u32x2*)(Z + (size_t)m * D + c) = w; }
;     }
.LBB0_1718:
	s_min_i32 s3, s22, 0x8000
	s_ashr_i32 s3, s3, 11
	global_load_dwordx4 v[64:67], v36, s[20:21]
	global_load_dwordx4 v[68:71], v36, s[20:21] offset:1024
	global_load_dwordx4 v[72:75], v36, s[20:21] offset:2048
	global_load_dwordx4 v[76:79], v36, s[20:21] offset:3072
	global_load_dwordx4 v[80:83], v[16:17], off
	v_mad_i64_i32 v[84:85], s[20:21], s3, v212, v[20:21]
	global_load_dwordx4 v[88:91], v[84:85], off
	v_mad_i64_i32 v[92:93], s[20:21], s3, v212, v[18:19]
	global_load_dwordx4 v[96:99], v[92:93], off
	global_load_dwordx4 v[100:103], v[16:17], off offset:1024
	global_load_dwordx4 v[104:107], v[92:93], off offset:1024
	global_load_dwordx4 v[108:111], v[84:85], off offset:1024
	global_load_dwordx4 v[112:115], v[16:17], off offset:2048
	global_load_dwordx4 v[116:119], v[92:93], off offset:2048
	global_load_dwordx4 v[120:123], v[84:85], off offset:2048
	global_load_dwordx4 v[124:127], v[16:17], off offset:3072
	global_load_dwordx4 v[128:131], v[92:93], off offset:3072
	global_load_dwordx4 v[132:135], v[84:85], off offset:3072
	s_lshl_b64 s[18:19], s[18:19], 11
	s_add_i32 s86, s86, s80
	s_waitcnt vmcnt(15)
	v_pk_mul_f32 v[0:1], v[66:67], v[66:67]
	v_pk_mul_f32 v[2:3], v[64:65], v[64:65]
	s_nop 0
	v_pk_mov_b32 v[4:5], v[2:3], v[0:1] op_sel:[1,0]
	v_mov_b32_e32 v3, v1
	v_pk_add_f32 v[26:27], v[4:5], v[2:3]
	s_waitcnt vmcnt(14)
	v_pk_mul_f32 v[0:1], v[70:71], v[70:71]
	v_pk_mul_f32 v[2:3], v[68:69], v[68:69]
	v_pk_add_f32 v[26:27], v[26:27], v[26:27] op_sel:[0,1] op_sel_hi:[1,0]
	v_pk_mov_b32 v[4:5], v[2:3], v[0:1] op_sel:[1,0]
	v_mov_b32_e32 v3, v1
	v_pk_add_f32 v[28:29], v[4:5], v[2:3]
	v_pk_add_f32 v[28:29], v[28:29], v[28:29] op_sel:[0,1] op_sel_hi:[1,0]
	s_waitcnt vmcnt(12)
	v_mul_f32_e32 v24, v76, v76
	v_mul_f32_e32 v37, v77, v77
	v_mov_b32_e32 v27, v24
	v_mov_b32_e32 v29, v37
	v_mul_f32_e32 v24, v73, v73
	v_mul_f32_e32 v38, v78, v78
	v_pk_add_f32 v[26:27], v[26:27], v[28:29]
	v_pk_fma_f32 v[28:29], v[72:73], v[72:73], v[24:25] op_sel_hi:[1,1,0]
	v_mul_f32_e32 v24, v75, v75
	v_mul_f32_e32 v40, v79, v79
	v_mov_b32_e32 v29, v38
	v_pk_fma_f32 v[38:39], v[74:75], v[74:75], v[24:25] op_sel_hi:[1,1,0]
	s_nop 0
	v_mov_b32_e32 v39, v40
	v_pk_add_f32 v[28:29], v[28:29], v[38:39]
	v_pk_add_f32 v[26:27], v[26:27], v[28:29]
	v_add_f32_e32 v24, v26, v27
	s_nop 1
	v_add_f32_dpp v24, v24, v24 quad_perm:[1,0,3,2] row_mask:0xf bank_mask:0xf
	s_nop 1
	v_add_f32_dpp v24, v24, v24 quad_perm:[2,3,0,1] row_mask:0xf bank_mask:0xf
	s_nop 1
	v_add_f32_dpp v24, v24, v24 row_half_mirror row_mask:0xf bank_mask:0xf
	s_nop 1
	v_add_f32_dpp v24, v24, v24 row_mirror row_mask:0xf bank_mask:0xf
	v_mov_b32_e32 v26, v24
	s_nop 1
	v_permlane16_swap_b32_e32 v24, v26
	v_add_f32_e32 v24, v24, v26
	v_mov_b32_e32 v26, v24
	s_nop 1
	v_permlane32_swap_b32_e32 v24, v26
	v_add_f32_e32 v24, v24, v26
	s_waitcnt lgkmcnt(0)
	v_fmamk_f32 v24, v24, 0x3a800000, v199
	v_cmp_gt_f32_e32 vcc, s64, v24
	v_mul_f32_e32 v26, 0x4b800000, v24
	s_nop 0
	v_cndmask_b32_e32 v24, v24, v26, vcc
	v_rsq_f32_e32 v24, v24
	s_nop 0
	v_mul_f32_e32 v26, 0x45800000, v24
	v_cndmask_b32_e32 v24, v24, v26, vcc
	v_pk_mul_f32 v[66:67], v[66:67], v[24:25] op_sel_hi:[1,0]
	v_pk_mul_f32 v[64:65], v[64:65], v[24:25] op_sel_hi:[1,0]
	v_pk_mul_f32 v[70:71], v[70:71], v[24:25] op_sel_hi:[1,0]
	v_pk_mul_f32 v[68:69], v[68:69], v[24:25] op_sel_hi:[1,0]
	v_pk_mul_f32 v[74:75], v[74:75], v[24:25] op_sel_hi:[1,0]
	v_pk_mul_f32 v[72:73], v[72:73], v[24:25] op_sel_hi:[1,0]
	s_add_i32 s3, s86, 0x8000
	s_add_u32 s14, s14, s80
	v_pk_mul_f32 v[78:79], v[78:79], v[24:25] op_sel_hi:[1,0]
	v_pk_mul_f32 v[76:77], v[76:77], v[24:25] op_sel_hi:[1,0]
	s_addc_u32 s15, s15, s81
	s_waitcnt vmcnt(11)
	v_pk_mul_f32 v[64:65], v[80:81], v[64:65]
	v_pk_mul_f32 v[66:67], v[82:83], v[66:67]
	s_waitcnt vmcnt(10)
	v_pk_add_f32 v[80:81], v[90:91], 1.0 op_sel_hi:[1,0]
	v_pk_add_f32 v[82:83], v[88:89], 1.0 op_sel_hi:[1,0]
	v_lshl_add_u64 v[88:89], v[22:23], 0, s[18:19]
	v_readlane_b32 s18, v255, 27
	v_readlane_b32 s19, v255, 28
	s_add_u32 s16, s16, s18
	s_addc_u32 s17, s17, s19
	s_cmp_gt_i32 s3, 0x8fff
	s_waitcnt vmcnt(9)
	v_pk_fma_f32 v[66:67], v[80:81], v[66:67], v[98:99]
	v_pk_fma_f32 v[64:65], v[82:83], v[64:65], v[96:97]
	s_nop 0
	v_cvt_pk_bf16_f32 v64, v64, v65
	v_cvt_pk_bf16_f32 v65, v66, v67
	global_store_dwordx2 v[88:89], v[64:65], off
	s_nop 0
	s_waitcnt vmcnt(9)
	v_pk_mul_f32 v[68:69], v[100:101], v[68:69]
	v_pk_mul_f32 v[70:71], v[102:103], v[70:71]
	s_waitcnt vmcnt(7)
	v_pk_add_f32 v[100:101], v[110:111], 1.0 op_sel_hi:[1,0]
	v_pk_add_f32 v[102:103], v[108:109], 1.0 op_sel_hi:[1,0]
	v_pk_fma_f32 v[70:71], v[100:101], v[70:71], v[106:107]
	v_pk_fma_f32 v[68:69], v[102:103], v[68:69], v[104:105]
	s_nop 0
	v_cvt_pk_bf16_f32 v68, v68, v69
	v_cvt_pk_bf16_f32 v69, v70, v71
	global_store_dwordx2 v[88:89], v[68:69], off offset:512
	s_nop 0
	s_waitcnt vmcnt(7)
	v_pk_mul_f32 v[72:73], v[112:113], v[72:73]
	v_pk_mul_f32 v[74:75], v[114:115], v[74:75]
	s_waitcnt vmcnt(5)
	v_pk_add_f32 v[112:113], v[122:123], 1.0 op_sel_hi:[1,0]
	v_pk_add_f32 v[114:115], v[120:121], 1.0 op_sel_hi:[1,0]
	v_pk_fma_f32 v[74:75], v[112:113], v[74:75], v[118:119]
	v_pk_fma_f32 v[72:73], v[114:115], v[72:73], v[116:117]
	s_nop 0
	v_cvt_pk_bf16_f32 v72, v72, v73
	v_cvt_pk_bf16_f32 v73, v74, v75
	global_store_dwordx2 v[88:89], v[72:73], off offset:1024
	s_nop 0
	s_waitcnt vmcnt(5)
	v_pk_mul_f32 v[124:125], v[124:125], v[76:77]
	v_pk_mul_f32 v[126:127], v[126:127], v[78:79]
	s_waitcnt vmcnt(3)
	v_pk_add_f32 v[76:77], v[134:135], 1.0 op_sel_hi:[1,0]
	v_pk_add_f32 v[78:79], v[132:133], 1.0 op_sel_hi:[1,0]
	v_pk_fma_f32 v[126:127], v[126:127], v[76:77], v[130:131]
	v_pk_fma_f32 v[124:125], v[124:125], v[78:79], v[128:129]
	s_nop 0
	v_cvt_pk_bf16_f32 v124, v124, v125
	v_cvt_pk_bf16_f32 v125, v126, v127
	global_store_dwordx2 v[88:89], v[124:125], off offset:1536
	s_cbranch_scc1 .LBB0_1721

; __device__ __forceinline__ unsigned pk2(float lo, float hi) { f32x2_pk v = {lo, hi}; bf16x2_pk b = __builtin_convertvector(v, bf16x2_pk); return __builtin_bit_cast(unsigned, b); }
; __device__ __forceinline__ void norm_phase(const float* xl, const float* xc, const float* g, const float* shift, const float* scale, bf16_t* Z, int row_lo, int nrows, int gw, int ngw, int lane) {
;     for (int m = row_lo + gw; m < nrows; m += ngw) {
;         const float* xr = m < ML ? xl + (size_t)m * D : xc + (size_t)(m - ML) * D; const int mr = m < ML ? (m >> 11) : 16;
;         f32x4 v[4]; float ss = 0.f;
; #pragma unroll
;         for (int j = 0; j < 4; ++j) { v[j] = *(const f32x4*)(xr + 4 * lane + 256 * j); ss += (v[j].x * v[j].x + v[j].y * v[j].y) + (v[j].z * v[j].z + v[j].w * v[j].w); }
;         const float ri = rsqrtf(wave_sum(ss) * (1.0f / D) + 1e-6f);
; #pragma unroll
;         for (int j = 0; j < 4; ++j) { const int c = 4 * lane + 256 * j; const f32x4 gv = *(const f32x4*)(g + c), sh = *(const f32x4*)(shift + (size_t)mr * 6144 + c), sc = *(const f32x4*)(scale + (size_t)mr * 6144 + c);
;             const f32x4 o = v[j] * ri * gv * (sc + 1.0f) + sh; u32x2 w; w.x = pk2(o.x, o.y); w.y = pk2(o.z, o.w); *(u32x2*)(Z + (size_t)m * D + c) = w; }
;     }
.LBB0_1725:
	s_ashr_i32 s1, s6, 11
	global_load_dwordx4 v[64:67], v[30:31], off offset:-2048
	global_load_dwordx4 v[68:71], v[30:31], off offset:-1024
	global_load_dwordx4 v[72:75], v[30:31], off
	global_load_dwordx4 v[76:79], v[30:31], off offset:1024
	global_load_dwordx4 v[80:83], v[16:17], off
	v_mad_i64_i32 v[84:85], s[2:3], s1, v212, v[26:27]
	global_load_dwordx4 v[88:91], v[84:85], off
	v_mad_i64_i32 v[92:93], s[2:3], s1, v212, v[24:25]
	global_load_dwordx4 v[96:99], v[92:93], off
	global_load_dwordx4 v[100:103], v[18:19], off
	global_load_dwordx4 v[104:107], v[92:93], off offset:1024
	global_load_dwordx4 v[108:111], v[84:85], off offset:1024
	global_load_dwordx4 v[112:115], v[20:21], off
	global_load_dwordx4 v[116:119], v[92:93], off offset:2048
	global_load_dwordx4 v[120:123], v[84:85], off offset:2048
	global_load_dwordx4 v[124:127], v[22:23], off
	global_load_dwordx4 v[128:131], v[92:93], off offset:3072
	global_load_dwordx4 v[132:135], v[84:85], off offset:3072
	s_add_i32 s6, s6, s80
	s_cmpk_gt_i32 s6, 0x7fff
	s_waitcnt vmcnt(15)
	v_pk_mul_f32 v[0:1], v[66:67], v[66:67]
	v_pk_mul_f32 v[2:3], v[64:65], v[64:65]
	s_nop 0
	v_pk_mov_b32 v[4:5], v[2:3], v[0:1] op_sel:[1,0]
	v_mov_b32_e32 v3, v1
	v_pk_add_f32 v[34:35], v[4:5], v[2:3]
	s_waitcnt vmcnt(14)
	v_pk_mul_f32 v[0:1], v[70:71], v[70:71]
	v_pk_mul_f32 v[2:3], v[68:69], v[68:69]
	v_pk_add_f32 v[34:35], v[34:35], v[34:35] op_sel:[0,1] op_sel_hi:[1,0]
	v_pk_mov_b32 v[4:5], v[2:3], v[0:1] op_sel:[1,0]
	v_mov_b32_e32 v3, v1
	v_pk_add_f32 v[36:37], v[4:5], v[2:3]
	v_pk_add_f32 v[36:37], v[36:37], v[36:37] op_sel:[0,1] op_sel_hi:[1,0]
	v_lshl_add_u64 v[30:31], v[30:31], 0, s[8:9]
	s_waitcnt vmcnt(12)
	v_mul_f32_e32 v32, v76, v76
	v_mul_f32_e32 v43, v77, v77
	v_mov_b32_e32 v35, v32
	v_mov_b32_e32 v37, v43
	v_mul_f32_e32 v32, v73, v73
	v_mul_f32_e32 v44, v78, v78
	v_pk_add_f32 v[34:35], v[34:35], v[36:37]
	v_pk_fma_f32 v[36:37], v[72:73], v[72:73], v[32:33] op_sel_hi:[1,1,0]
	v_mul_f32_e32 v32, v75, v75
	v_mul_f32_e32 v46, v79, v79
	v_mov_b32_e32 v37, v44
	v_pk_fma_f32 v[44:45], v[74:75], v[74:75], v[32:33] op_sel_hi:[1,1,0]
	s_nop 0
	v_mov_b32_e32 v45, v46
	v_pk_add_f32 v[36:37], v[36:37], v[44:45]
	v_pk_add_f32 v[34:35], v[34:35], v[36:37]
	v_add_f32_e32 v32, v34, v35
	s_nop 1
	v_add_f32_dpp v32, v32, v32 quad_perm:[1,0,3,2] row_mask:0xf bank_mask:0xf
	s_nop 1
	v_add_f32_dpp v32, v32, v32 quad_perm:[2,3,0,1] row_mask:0xf bank_mask:0xf
	s_nop 1
	v_add_f32_dpp v32, v32, v32 row_half_mirror row_mask:0xf bank_mask:0xf
	s_nop 1
	v_add_f32_dpp v32, v32, v32 row_mirror row_mask:0xf bank_mask:0xf
	v_mov_b32_e32 v34, v32
	s_nop 1
	v_permlane16_swap_b32_e32 v32, v34
	v_add_f32_e32 v32, v32, v34
	v_mov_b32_e32 v34, v32
	s_nop 1
	v_permlane32_swap_b32_e32 v32, v34
	v_add_f32_e32 v32, v32, v34
	s_waitcnt lgkmcnt(0)
	v_fmamk_f32 v32, v32, 0x3a800000, v199
	v_cmp_gt_f32_e32 vcc, s64, v32
	v_mul_f32_e32 v34, 0x4b800000, v32
	s_nop 0
	v_cndmask_b32_e32 v32, v32, v34, vcc
	v_rsq_f32_e32 v32, v32
	s_nop 0
	v_mul_f32_e32 v34, 0x45800000, v32
	v_cndmask_b32_e32 v32, v32, v34, vcc
	v_pk_mul_f32 v[66:67], v[66:67], v[32:33] op_sel_hi:[1,0]
	v_pk_mul_f32 v[64:65], v[64:65], v[32:33] op_sel_hi:[1,0]
	v_pk_mul_f32 v[70:71], v[70:71], v[32:33] op_sel_hi:[1,0]
	v_pk_mul_f32 v[68:69], v[68:69], v[32:33] op_sel_hi:[1,0]
	v_pk_mul_f32 v[74:75], v[74:75], v[32:33] op_sel_hi:[1,0]
	v_pk_mul_f32 v[72:73], v[72:73], v[32:33] op_sel_hi:[1,0]
	v_pk_mul_f32 v[78:79], v[78:79], v[32:33] op_sel_hi:[1,0]
	v_pk_mul_f32 v[76:77], v[76:77], v[32:33] op_sel_hi:[1,0]
	s_waitcnt vmcnt(11)
	v_pk_mul_f32 v[64:65], v[80:81], v[64:65]
	v_pk_mul_f32 v[66:67], v[82:83], v[66:67]
	s_waitcnt vmcnt(10)
	v_pk_add_f32 v[80:81], v[90:91], 1.0 op_sel_hi:[1,0]
	v_pk_add_f32 v[82:83], v[88:89], 1.0 op_sel_hi:[1,0]
	s_waitcnt vmcnt(9)
	v_pk_fma_f32 v[66:67], v[80:81], v[66:67], v[98:99]
	v_pk_fma_f32 v[64:65], v[82:83], v[64:65], v[96:97]
	s_nop 0
	v_cvt_pk_bf16_f32 v64, v64, v65
	v_cvt_pk_bf16_f32 v65, v66, v67
	global_store_dwordx2 v[28:29], v[64:65], off
	s_nop 0
	s_waitcnt vmcnt(9)
	v_pk_mul_f32 v[68:69], v[100:101], v[68:69]
	v_pk_mul_f32 v[70:71], v[102:103], v[70:71]
	s_waitcnt vmcnt(7)
	v_pk_add_f32 v[100:101], v[110:111], 1.0 op_sel_hi:[1,0]
	v_pk_add_f32 v[102:103], v[108:109], 1.0 op_sel_hi:[1,0]
	v_pk_fma_f32 v[70:71], v[100:101], v[70:71], v[106:107]
	v_pk_fma_f32 v[68:69], v[102:103], v[68:69], v[104:105]
	s_nop 0
	v_cvt_pk_bf16_f32 v68, v68, v69
	v_cvt_pk_bf16_f32 v69, v70, v71
	global_store_dwordx2 v[28:29], v[68:69], off offset:512
	s_nop 0
	s_waitcnt vmcnt(7)
	v_pk_mul_f32 v[72:73], v[112:113], v[72:73]
	v_pk_mul_f32 v[74:75], v[114:115], v[74:75]
	s_waitcnt vmcnt(5)
	v_pk_add_f32 v[112:113], v[122:123], 1.0 op_sel_hi:[1,0]
	v_pk_add_f32 v[114:115], v[120:121], 1.0 op_sel_hi:[1,0]
	v_pk_fma_f32 v[74:75], v[112:113], v[74:75], v[118:119]
	v_pk_fma_f32 v[72:73], v[114:115], v[72:73], v[116:117]
	s_nop 0
	v_cvt_pk_bf16_f32 v72, v72, v73
	v_cvt_pk_bf16_f32 v73, v74, v75
	global_store_dwordx2 v[28:29], v[72:73], off offset:1024
	s_nop 0
	s_waitcnt vmcnt(5)
	v_pk_mul_f32 v[124:125], v[124:125], v[76:77]
	v_pk_mul_f32 v[126:127], v[126:127], v[78:79]
	s_waitcnt vmcnt(3)
	v_pk_add_f32 v[76:77], v[134:135], 1.0 op_sel_hi:[1,0]
	v_pk_add_f32 v[78:79], v[132:133], 1.0 op_sel_hi:[1,0]
	v_pk_fma_f32 v[126:127], v[126:127], v[76:77], v[130:131]
	v_pk_fma_f32 v[124:125], v[124:125], v[78:79], v[128:129]
	s_nop 0
	v_cvt_pk_bf16_f32 v124, v124, v125
	v_cvt_pk_bf16_f32 v125, v126, v127
	global_store_dwordx2 v[28:29], v[124:125], off offset:1536
	v_lshl_add_u64 v[28:29], v[28:29], 0, s[10:11]
	s_cbranch_scc0 .LBB0_1725

; __device__ __forceinline__ unsigned pk2(float lo, float hi) { f32x2_pk v = {lo, hi}; bf16x2_pk b = __builtin_convertvector(v, bf16x2_pk); return __builtin_bit_cast(unsigned, b); }
; __device__ __forceinline__ void norm_phase(const float* xl, const float* xc, const float* g, const float* shift, const float* scale, bf16_t* Z, int row_lo, int nrows, int gw, int ngw, int lane) {
;     for (int m = row_lo + gw; m < nrows; m += ngw) {
;         const float* xr = m < ML ? xl + (size_t)m * D : xc + (size_t)(m - ML) * D; const int mr = m < ML ? (m >> 11) : 16;
;         f32x4 v[4]; float ss = 0.f;
; #pragma unroll
;         for (int j = 0; j < 4; ++j) { v[j] = *(const f32x4*)(xr + 4 * lane + 256 * j); ss += (v[j].x * v[j].x + v[j].y * v[j].y) + (v[j].z * v[j].z + v[j].w * v[j].w); }
;         const float ri = rsqrtf(wave_sum(ss) * (1.0f / D) + 1e-6f);
; #pragma unroll
;         for (int j = 0; j < 4; ++j) { const int c = 4 * lane + 256 * j; const f32x4 gv = *(const f32x4*)(g + c), sh = *(const f32x4*)(shift + (size_t)mr * 6144 + c), sc = *(const f32x4*)(scale + (size_t)mr * 6144 + c);
;             const f32x4 o = v[j] * ri * gv * (sc + 1.0f) + sh; u32x2 w; w.x = pk2(o.x, o.y); w.y = pk2(o.z, o.w); *(u32x2*)(Z + (size_t)m * D + c) = w; }
;     }
.LBB0_2115:
	s_min_i32 s3, s14, 0x8000
	s_ashr_i32 s3, s3, 11
	global_load_dwordx4 v[64:67], v35, s[12:13]
	global_load_dwordx4 v[68:71], v35, s[12:13] offset:1024
	global_load_dwordx4 v[72:75], v35, s[12:13] offset:2048
	global_load_dwordx4 v[76:79], v35, s[12:13] offset:3072
	global_load_dwordx4 v[80:83], v[16:17], off
	v_mad_i64_i32 v[84:85], s[12:13], s3, v212, v[20:21]
	global_load_dwordx4 v[88:91], v[84:85], off
	v_mad_i64_i32 v[92:93], s[12:13], s3, v212, v[18:19]
	global_load_dwordx4 v[96:99], v[92:93], off
	global_load_dwordx4 v[100:103], v[16:17], off offset:1024
	global_load_dwordx4 v[104:107], v[92:93], off offset:1024
	global_load_dwordx4 v[108:111], v[84:85], off offset:1024
	global_load_dwordx4 v[112:115], v[16:17], off offset:2048
	global_load_dwordx4 v[116:119], v[92:93], off offset:2048
	global_load_dwordx4 v[120:123], v[84:85], off offset:2048
	global_load_dwordx4 v[124:127], v[16:17], off offset:3072
	global_load_dwordx4 v[128:131], v[92:93], off offset:3072
	global_load_dwordx4 v[132:135], v[84:85], off offset:3072
	s_lshl_b64 s[10:11], s[10:11], 11
	s_add_i32 s86, s86, s80
	s_waitcnt vmcnt(15)
	v_pk_mul_f32 v[0:1], v[66:67], v[66:67]
	v_pk_mul_f32 v[2:3], v[64:65], v[64:65]
	s_nop 0
	v_pk_mov_b32 v[4:5], v[2:3], v[0:1] op_sel:[1,0]
	v_mov_b32_e32 v3, v1
	v_pk_add_f32 v[26:27], v[4:5], v[2:3]
	s_waitcnt vmcnt(14)
	v_pk_mul_f32 v[0:1], v[70:71], v[70:71]
	v_pk_mul_f32 v[2:3], v[68:69], v[68:69]
	v_pk_add_f32 v[26:27], v[26:27], v[26:27] op_sel:[0,1] op_sel_hi:[1,0]
	v_pk_mov_b32 v[4:5], v[2:3], v[0:1] op_sel:[1,0]
	v_mov_b32_e32 v3, v1
	v_pk_add_f32 v[28:29], v[4:5], v[2:3]
	v_pk_add_f32 v[28:29], v[28:29], v[28:29] op_sel:[0,1] op_sel_hi:[1,0]
	s_waitcnt vmcnt(12)
	v_mul_f32_e32 v24, v76, v76
	v_mul_f32_e32 v36, v77, v77
	v_mov_b32_e32 v27, v24
	v_mov_b32_e32 v29, v36
	v_mul_f32_e32 v24, v73, v73
	v_mul_f32_e32 v37, v78, v78
	v_pk_add_f32 v[26:27], v[26:27], v[28:29]
	v_pk_fma_f32 v[28:29], v[72:73], v[72:73], v[24:25] op_sel_hi:[1,1,0]
	v_mul_f32_e32 v24, v75, v75
	v_mul_f32_e32 v38, v79, v79
	v_mov_b32_e32 v29, v37
	v_pk_fma_f32 v[36:37], v[74:75], v[74:75], v[24:25] op_sel_hi:[1,1,0]
	s_nop 0
	v_mov_b32_e32 v37, v38
	v_pk_add_f32 v[28:29], v[28:29], v[36:37]
	v_pk_add_f32 v[26:27], v[26:27], v[28:29]
	v_add_f32_e32 v24, v26, v27
	s_nop 1
	v_add_f32_dpp v24, v24, v24 quad_perm:[1,0,3,2] row_mask:0xf bank_mask:0xf
	s_nop 1
	v_add_f32_dpp v24, v24, v24 quad_perm:[2,3,0,1] row_mask:0xf bank_mask:0xf
	s_nop 1
	v_add_f32_dpp v24, v24, v24 row_half_mirror row_mask:0xf bank_mask:0xf
	s_nop 1
	v_add_f32_dpp v24, v24, v24 row_mirror row_mask:0xf bank_mask:0xf
	v_mov_b32_e32 v26, v24
	s_nop 1
	v_permlane16_swap_b32_e32 v24, v26
	v_add_f32_e32 v24, v24, v26
	v_mov_b32_e32 v26, v24
	s_nop 1
	v_permlane32_swap_b32_e32 v24, v26
	v_add_f32_e32 v24, v24, v26
	s_waitcnt lgkmcnt(0)
	v_fmamk_f32 v24, v24, 0x3a800000, v199
	v_cmp_gt_f32_e32 vcc, s64, v24
	v_mul_f32_e32 v26, 0x4b800000, v24
	s_nop 0
	v_cndmask_b32_e32 v24, v24, v26, vcc
	v_rsq_f32_e32 v24, v24
	s_nop 0
	v_mul_f32_e32 v26, 0x45800000, v24
	v_cndmask_b32_e32 v24, v24, v26, vcc
	v_pk_mul_f32 v[66:67], v[66:67], v[24:25] op_sel_hi:[1,0]
	v_pk_mul_f32 v[64:65], v[64:65], v[24:25] op_sel_hi:[1,0]
	v_pk_mul_f32 v[70:71], v[70:71], v[24:25] op_sel_hi:[1,0]
	v_pk_mul_f32 v[68:69], v[68:69], v[24:25] op_sel_hi:[1,0]
	v_pk_mul_f32 v[74:75], v[74:75], v[24:25] op_sel_hi:[1,0]
	v_pk_mul_f32 v[72:73], v[72:73], v[24:25] op_sel_hi:[1,0]
	s_add_i32 s3, s86, 0x8000
	s_add_u32 s6, s6, s80
	v_pk_mul_f32 v[78:79], v[78:79], v[24:25] op_sel_hi:[1,0]
	v_pk_mul_f32 v[76:77], v[76:77], v[24:25] op_sel_hi:[1,0]
	s_addc_u32 s7, s7, s81
	s_add_u32 s8, s8, s48
	s_addc_u32 s9, s9, s49
	s_cmp_lt_i32 s3, 0x9000
	s_waitcnt vmcnt(11)
	v_pk_mul_f32 v[64:65], v[80:81], v[64:65]
	v_pk_mul_f32 v[66:67], v[82:83], v[66:67]
	s_waitcnt vmcnt(10)
	v_pk_add_f32 v[80:81], v[90:91], 1.0 op_sel_hi:[1,0]
	v_pk_add_f32 v[82:83], v[88:89], 1.0 op_sel_hi:[1,0]
	v_lshl_add_u64 v[88:89], v[22:23], 0, s[10:11]
	s_waitcnt vmcnt(9)
	v_pk_fma_f32 v[66:67], v[80:81], v[66:67], v[98:99]
	v_pk_fma_f32 v[64:65], v[82:83], v[64:65], v[96:97]
	s_nop 0
	v_cvt_pk_bf16_f32 v64, v64, v65
	v_cvt_pk_bf16_f32 v65, v66, v67
	global_store_dwordx2 v[88:89], v[64:65], off
	s_nop 0
	s_waitcnt vmcnt(9)
	v_pk_mul_f32 v[68:69], v[100:101], v[68:69]
	v_pk_mul_f32 v[70:71], v[102:103], v[70:71]
	s_waitcnt vmcnt(7)
	v_pk_add_f32 v[100:101], v[110:111], 1.0 op_sel_hi:[1,0]
	v_pk_add_f32 v[102:103], v[108:109], 1.0 op_sel_hi:[1,0]
	v_pk_fma_f32 v[70:71], v[100:101], v[70:71], v[106:107]
	v_pk_fma_f32 v[68:69], v[102:103], v[68:69], v[104:105]
	s_nop 0
	v_cvt_pk_bf16_f32 v68, v68, v69
	v_cvt_pk_bf16_f32 v69, v70, v71
	global_store_dwordx2 v[88:89], v[68:69], off offset:512
	s_nop 0
	s_waitcnt vmcnt(7)
	v_pk_mul_f32 v[72:73], v[112:113], v[72:73]
	v_pk_mul_f32 v[74:75], v[114:115], v[74:75]
	s_waitcnt vmcnt(5)
	v_pk_add_f32 v[112:113], v[122:123], 1.0 op_sel_hi:[1,0]
	v_pk_add_f32 v[114:115], v[120:121], 1.0 op_sel_hi:[1,0]
	v_pk_fma_f32 v[74:75], v[112:113], v[74:75], v[118:119]
	v_pk_fma_f32 v[72:73], v[114:115], v[72:73], v[116:117]
	s_nop 0
	v_cvt_pk_bf16_f32 v72, v72, v73
	v_cvt_pk_bf16_f32 v73, v74, v75
	global_store_dwordx2 v[88:89], v[72:73], off offset:1024
	s_nop 0
	s_waitcnt vmcnt(5)
	v_pk_mul_f32 v[124:125], v[124:125], v[76:77]
	v_pk_mul_f32 v[126:127], v[126:127], v[78:79]
	s_waitcnt vmcnt(3)
	v_pk_add_f32 v[76:77], v[134:135], 1.0 op_sel_hi:[1,0]
	v_pk_add_f32 v[78:79], v[132:133], 1.0 op_sel_hi:[1,0]
	v_pk_fma_f32 v[126:127], v[126:127], v[76:77], v[130:131]
	v_pk_fma_f32 v[124:125], v[124:125], v[78:79], v[128:129]
	s_nop 0
	v_cvt_pk_bf16_f32 v124, v124, v125
	v_cvt_pk_bf16_f32 v125, v126, v127
	global_store_dwordx2 v[88:89], v[124:125], off offset:1536
	s_cbranch_scc0 .LBB0_2118

; __device__ __forceinline__ void final_norm_phase(float* x, const float* g, int gw, int ngw, int lane) {
;     for (int m = gw; m < ML; m += ngw) { float* xr = x + (size_t)m * D; f32x4 v[4]; float ss = 0.f;
; #pragma unroll
;         for (int j = 0; j < 4; ++j) { v[j] = *(const f32x4*)(xr + 4 * lane + 256 * j); ss += (v[j].x * v[j].x + v[j].y * v[j].y) + (v[j].z * v[j].z + v[j].w * v[j].w); }
;         const float ri = rsqrtf(wave_sum(ss) * (1.0f / D) + 1e-6f);
; #pragma unroll
;         for (int j = 0; j < 4; ++j) { const int c = 4 * lane + 256 * j; *(f32x4*)(xr + c) = v[j] * ri * *(const f32x4*)(g + c); } }
; }
.LBB0_2181:
	s_cmp_le_i32 s70, s75
	s_cselect_b64 s[0:1], -1, 0
	s_cmp_lt_i32 s75, s71
	s_cselect_b64 s[2:3], -1, 0
	s_and_b64 s[0:1], s[0:1], s[2:3]
	s_and_b64 vcc, exec, s[0:1]
	s_cbranch_vccz .LBB0_2185
	s_lshl_b32 s1, s91, 3
	v_readfirstlane_b32 s0, v198
	s_ashr_i32 s0, s0, 6
	s_add_i32 s2, s1, s0
	s_cmpk_gt_i32 s2, 0x7fff
	s_cbranch_scc1 .LBB0_2185
	v_cmp_lt_i32_e32 vcc, v210, v204
	s_load_dwordx4 s[4:7], s[84:85], 0x118
	s_ashr_i32 s3, s2, 31
	v_cndmask_b32_e32 v0, v203, v210, vcc
	v_cmp_lt_i32_e32 vcc, v209, v204
	v_lshlrev_b32_e32 v4, 2, v0
	v_mov_b32_e32 v3, 0
	v_cndmask_b32_e32 v0, v203, v209, vcc
	v_cmp_lt_i32_e32 vcc, v208, v204
	v_lshlrev_b32_e32 v5, 2, v0
	s_lshl_b64 s[0:1], s[2:3], 12
	v_cndmask_b32_e32 v0, v203, v208, vcc
	v_cmp_lt_i32_e32 vcc, v207, v204
	v_lshlrev_b32_e32 v6, 2, v0
	s_waitcnt lgkmcnt(0)
	s_add_u32 s0, s6, s0
	v_cndmask_b32_e32 v0, v203, v207, vcc
	v_cmp_lt_i32_e32 vcc, v206, v204
	v_lshlrev_b32_e32 v7, 2, v0
	s_addc_u32 s1, s7, s1
	v_cndmask_b32_e32 v0, v203, v206, vcc
	v_cmp_lt_i32_e32 vcc, v205, v204
	v_lshlrev_b32_e32 v8, 2, v0
	v_mov_b32_e32 v10, 0x358637bd
	v_cndmask_b32_e32 v0, v203, v205, vcc
	v_lshlrev_b32_e32 v9, 2, v0
	v_lshlrev_b32_e32 v0, 4, v198
	v_and_b32_e32 v2, 0x3f0, v0
	v_lshl_add_u64 v[0:1], s[4:5], 0, v[2:3]
	v_and_b32_e32 v2, 63, v198
	v_lshlrev_b32_e32 v2, 4, v2
	v_lshl_add_u64 v[2:3], s[0:1], 0, v[2:3]
	s_mov_b64 s[0:1], 0x800
	v_lshl_add_u64 v[2:3], v[2:3], 0, s[0:1]
	s_mov_b32 s0, 0x800000
	global_load_dwordx4 v[48:51], v[0:1], off
	global_load_dwordx4 v[52:55], v[0:1], off offset:1024
	global_load_dwordx4 v[56:59], v[0:1], off offset:2048
	global_load_dwordx4 v[60:63], v[0:1], off offset:3072
	global_load_dwordx4 v[12:15], v[2:3], off offset:-2048
	global_load_dwordx4 v[16:19], v[2:3], off offset:-1024
	global_load_dwordx4 v[20:23], v[2:3], off offset:1024
	global_load_dwordx4 v[24:27], v[2:3], off
.LBB0_2184:
	v_lshl_add_u64 v[4:5], v[2:3], 0, s[48:49]
	global_load_dwordx4 v[64:67], v[4:5], off offset:-2048
	global_load_dwordx4 v[68:71], v[4:5], off offset:-1024
	global_load_dwordx4 v[72:75], v[4:5], off offset:1024
	global_load_dwordx4 v[76:79], v[4:5], off
	s_waitcnt vmcnt(4)
	v_pk_mul_f32 v[32:33], v[14:15], v[14:15]
	v_pk_mul_f32 v[34:35], v[12:13], v[12:13]
	v_pk_mul_f32 v[36:37], v[18:19], v[18:19]
	v_pk_mul_f32 v[38:39], v[16:17], v[16:17]
	v_pk_mov_b32 v[44:45], v[34:35], v[32:33] op_sel:[1,0]
	v_mov_b32_e32 v35, v33
	v_pk_mov_b32 v[32:33], v[38:39], v[36:37] op_sel:[1,0]
	v_mov_b32_e32 v39, v37
	v_mul_f32_e32 v43, v21, v21
	v_mul_f32_e32 v40, v25, v25
	v_mul_f32_e32 v42, v27, v27
	v_pk_add_f32 v[34:35], v[44:45], v[34:35]
	v_pk_add_f32 v[32:33], v[32:33], v[38:39]
	v_mul_f32_e32 v11, v20, v20
	v_mul_f32_e32 v46, v22, v22
	v_mul_f32_e32 v47, v23, v23
	v_pk_fma_f32 v[36:37], v[24:25], v[24:25], v[40:41] op_sel_hi:[1,1,0]
	v_pk_fma_f32 v[40:41], v[26:27], v[26:27], v[42:43] op_sel_hi:[1,1,0]
	v_pk_add_f32 v[34:35], v[34:35], v[34:35] op_sel:[0,1] op_sel_hi:[1,0]
	v_pk_add_f32 v[32:33], v[32:33], v[32:33] op_sel:[0,1] op_sel_hi:[1,0]
	v_mov_b32_e32 v37, v46
	v_mov_b32_e32 v41, v47
	v_mov_b32_e32 v35, v11
	v_mov_b32_e32 v33, v43
	v_pk_add_f32 v[36:37], v[36:37], v[40:41]
	v_pk_add_f32 v[32:33], v[34:35], v[32:33]
	s_nop 0
	v_pk_add_f32 v[32:33], v[32:33], v[36:37]
	s_nop 0
	v_add_f32_e32 v11, v32, v33
	s_nop 1
	v_add_f32_dpp v11, v11, v11 quad_perm:[1,0,3,2] row_mask:0xf bank_mask:0xf
	s_nop 1
	v_add_f32_dpp v11, v11, v11 quad_perm:[2,3,0,1] row_mask:0xf bank_mask:0xf
	s_nop 1
	v_add_f32_dpp v11, v11, v11 row_half_mirror row_mask:0xf bank_mask:0xf
	s_nop 1
	v_add_f32_dpp v11, v11, v11 row_mirror row_mask:0xf bank_mask:0xf
	v_mov_b32_e32 v32, v11
	s_nop 1
	v_permlane16_swap_b32_e32 v11, v32
	v_add_f32_e32 v11, v11, v32
	v_mov_b32_e32 v32, v11
	s_nop 1
	v_permlane32_swap_b32_e32 v11, v32
	v_add_f32_e32 v11, v11, v32
	v_fmamk_f32 v11, v11, 0x3a800000, v10
	v_mul_f32_e32 v32, 0x4b800000, v11
	v_cmp_gt_f32_e32 vcc, s0, v11
	s_nop 1
	v_cndmask_b32_e32 v11, v11, v32, vcc
	v_rsq_f32_e32 v11, v11
	s_nop 0
	v_mul_f32_e32 v32, 0x45800000, v11
	v_cndmask_b32_e32 v32, v11, v32, vcc
	v_pk_mul_f32 v[12:13], v[12:13], v[32:33] op_sel_hi:[1,0]
	v_pk_mul_f32 v[14:15], v[14:15], v[32:33] op_sel_hi:[1,0]
	v_pk_mul_f32 v[12:13], v[48:49], v[12:13]
	v_pk_mul_f32 v[14:15], v[50:51], v[14:15]
	global_store_dwordx4 v[2:3], v[12:15], off offset:-2048
	v_pk_mul_f32 v[16:17], v[16:17], v[32:33] op_sel_hi:[1,0]
	v_pk_mul_f32 v[18:19], v[18:19], v[32:33] op_sel_hi:[1,0]
	v_pk_mul_f32 v[16:17], v[52:53], v[16:17]
	v_pk_mul_f32 v[18:19], v[54:55], v[18:19]
	global_store_dwordx4 v[2:3], v[16:19], off offset:-1024
	v_pk_mul_f32 v[24:25], v[24:25], v[32:33] op_sel_hi:[1,0]
	v_pk_mul_f32 v[26:27], v[26:27], v[32:33] op_sel_hi:[1,0]
	v_pk_mul_f32 v[24:25], v[56:57], v[24:25]
	v_pk_mul_f32 v[26:27], v[58:59], v[26:27]
	global_store_dwordx4 v[2:3], v[24:27], off
	v_pk_mul_f32 v[20:21], v[20:21], v[32:33] op_sel_hi:[1,0]
	v_pk_mul_f32 v[22:23], v[22:23], v[32:33] op_sel_hi:[1,0]
	v_pk_mul_f32 v[20:21], v[60:61], v[20:21]
	v_pk_mul_f32 v[22:23], v[62:63], v[22:23]
	global_store_dwordx4 v[2:3], v[20:23], off offset:1024
	v_lshl_add_u64 v[2:3], v[4:5], 0, s[48:49]
	s_add_i32 s2, s2, s80
	s_add_i32 s2, s2, s80
	s_cmp_lt_i32 s2, 0x8000
	s_cbranch_scc0 .Lfn_last
	global_load_dwordx4 v[12:15], v[2:3], off offset:-2048
	global_load_dwordx4 v[16:19], v[2:3], off offset:-1024
	global_load_dwordx4 v[20:23], v[2:3], off offset:1024
	global_load_dwordx4 v[24:27], v[2:3], off
	s_waitcnt vmcnt(8)
	s_branch .Lfn_B
; __device__ __forceinline__ void final_norm_phase(float* x, const float* g, int gw, int ngw, int lane) {
;     for (int m = gw; m < ML; m += ngw) { float* xr = x + (size_t)m * D; f32x4 v[4]; float ss = 0.f;
; #pragma unroll
;         for (int j = 0; j < 4; ++j) { v[j] = *(const f32x4*)(xr + 4 * lane + 256 * j); ss += (v[j].x * v[j].x + v[j].y * v[j].y) + (v[j].z * v[j].z + v[j].w * v[j].w); }
;         const float ri = rsqrtf(wave_sum(ss) * (1.0f / D) + 1e-6f);
; #pragma unroll
;         for (int j = 0; j < 4; ++j) { const int c = 4 * lane + 256 * j; *(f32x4*)(xr + c) = v[j] * ri * *(const f32x4*)(g + c); } }
; }
.Lfn_last:
	s_waitcnt vmcnt(4)
.Lfn_B:
	v_pk_mul_f32 v[32:33], v[66:67], v[66:67]
	v_pk_mul_f32 v[34:35], v[64:65], v[64:65]
	v_pk_mul_f32 v[36:37], v[70:71], v[70:71]
	v_pk_mul_f32 v[38:39], v[68:69], v[68:69]
	v_pk_mov_b32 v[44:45], v[34:35], v[32:33] op_sel:[1,0]
	v_mov_b32_e32 v35, v33
	v_pk_mov_b32 v[32:33], v[38:39], v[36:37] op_sel:[1,0]
	v_mov_b32_e32 v39, v37
	v_mul_f32_e32 v43, v73, v73
	v_mul_f32_e32 v40, v77, v77
	v_mul_f32_e32 v42, v79, v79
	v_pk_add_f32 v[34:35], v[44:45], v[34:35]
	v_pk_add_f32 v[32:33], v[32:33], v[38:39]
	v_mul_f32_e32 v11, v72, v72
	v_mul_f32_e32 v46, v74, v74
	v_mul_f32_e32 v47, v75, v75
	v_pk_fma_f32 v[36:37], v[76:77], v[76:77], v[40:41] op_sel_hi:[1,1,0]
	v_pk_fma_f32 v[40:41], v[78:79], v[78:79], v[42:43] op_sel_hi:[1,1,0]
	v_pk_add_f32 v[34:35], v[34:35], v[34:35] op_sel:[0,1] op_sel_hi:[1,0]
	v_pk_add_f32 v[32:33], v[32:33], v[32:33] op_sel:[0,1] op_sel_hi:[1,0]
	v_mov_b32_e32 v37, v46
	v_mov_b32_e32 v41, v47
	v_mov_b32_e32 v35, v11
	v_mov_b32_e32 v33, v43
	v_pk_add_f32 v[36:37], v[36:37], v[40:41]
	v_pk_add_f32 v[32:33], v[34:35], v[32:33]
	s_nop 0
	v_pk_add_f32 v[32:33], v[32:33], v[36:37]
	s_nop 0
	v_add_f32_e32 v11, v32, v33
	s_nop 1
	v_add_f32_dpp v11, v11, v11 quad_perm:[1,0,3,2] row_mask:0xf bank_mask:0xf
	s_nop 1
	v_add_f32_dpp v11, v11, v11 quad_perm:[2,3,0,1] row_mask:0xf bank_mask:0xf
	s_nop 1
	v_add_f32_dpp v11, v11, v11 row_half_mirror row_mask:0xf bank_mask:0xf
	s_nop 1
	v_add_f32_dpp v11, v11, v11 row_mirror row_mask:0xf bank_mask:0xf
	v_mov_b32_e32 v32, v11
	s_nop 1
	v_permlane16_swap_b32_e32 v11, v32
	v_add_f32_e32 v11, v11, v32
	v_mov_b32_e32 v32, v11
	s_nop 1
	v_permlane32_swap_b32_e32 v11, v32
	v_add_f32_e32 v11, v11, v32
	v_fmamk_f32 v11, v11, 0x3a800000, v10
	v_mul_f32_e32 v32, 0x4b800000, v11
	v_cmp_gt_f32_e32 vcc, s0, v11
	s_nop 1
	v_cndmask_b32_e32 v11, v11, v32, vcc
	v_rsq_f32_e32 v11, v11
	s_nop 0
	v_mul_f32_e32 v32, 0x45800000, v11
	v_cndmask_b32_e32 v32, v11, v32, vcc
	v_pk_mul_f32 v[64:65], v[64:65], v[32:33] op_sel_hi:[1,0]
	v_pk_mul_f32 v[66:67], v[66:67], v[32:33] op_sel_hi:[1,0]
	v_pk_mul_f32 v[64:65], v[48:49], v[64:65]
	v_pk_mul_f32 v[66:67], v[50:51], v[66:67]
	global_store_dwordx4 v[4:5], v[64:67], off offset:-2048
	v_pk_mul_f32 v[68:69], v[68:69], v[32:33] op_sel_hi:[1,0]
	v_pk_mul_f32 v[70:71], v[70:71], v[32:33] op_sel_hi:[1,0]
	v_pk_mul_f32 v[68:69], v[52:53], v[68:69]
	v_pk_mul_f32 v[70:71], v[54:55], v[70:71]
	global_store_dwordx4 v[4:5], v[68:71], off offset:-1024
	v_pk_mul_f32 v[76:77], v[76:77], v[32:33] op_sel_hi:[1,0]
	v_pk_mul_f32 v[78:79], v[78:79], v[32:33] op_sel_hi:[1,0]
	v_pk_mul_f32 v[76:77], v[56:57], v[76:77]
	v_pk_mul_f32 v[78:79], v[58:59], v[78:79]
	global_store_dwordx4 v[4:5], v[76:79], off
	v_pk_mul_f32 v[72:73], v[72:73], v[32:33] op_sel_hi:[1,0]
	v_pk_mul_f32 v[74:75], v[74:75], v[32:33] op_sel_hi:[1,0]
	v_pk_mul_f32 v[72:73], v[60:61], v[72:73]
	v_pk_mul_f32 v[74:75], v[62:63], v[74:75]
	global_store_dwordx4 v[4:5], v[72:75], off offset:1024
	s_cbranch_scc1 .LBB0_2184
